# phase0 adaLN mat-vec: 16 weight-row loads in flight per iteration (was 4 with full drain)
# baseline (speedup 1.0000x reference)
; DI void phase0(const Params& p, char* smem) {
;     ...
;     const float* wp = p.w_ada + (size_t)l * 1024 * 6144 + col;
; #pragma unroll 4
;     for (int k = w * 128; k < w * 128 + 128; ++k) {
;       const float wv = wp[(size_t)k * 6144];
; #pragma unroll
;       for (int r = 0; r < 9; ++r) a[r] += sc[r * 1024 + k] * wv;
;     }
.LBB0_36:
	v_lshl_add_u64 v[30:31], v[10:11], 0, s[16:17]
	global_load_dword v84, v[30:31], off
	v_add_co_u32_e32 v32, vcc, 0x6000, v30
	s_nop 1
	v_addc_co_u32_e32 v33, vcc, 0, v31, vcc
	global_load_dword v86, v[32:33], off
	v_add_co_u32_e32 v34, vcc, 0xc000, v30
	s_nop 1
	v_addc_co_u32_e32 v35, vcc, 0, v31, vcc
	global_load_dword v88, v[34:35], off
	v_add_co_u32_e32 v32, vcc, 0x12000, v30
	s_nop 1
	v_addc_co_u32_e32 v33, vcc, 0, v31, vcc
	global_load_dword v90, v[32:33], off
	v_add_co_u32_e32 v34, vcc, 0x18000, v30
	s_nop 1
	v_addc_co_u32_e32 v35, vcc, 0, v31, vcc
	global_load_dword v92, v[34:35], off
	v_add_co_u32_e32 v32, vcc, 0x1e000, v30
	s_nop 1
	v_addc_co_u32_e32 v33, vcc, 0, v31, vcc
	global_load_dword v94, v[32:33], off
	v_add_co_u32_e32 v34, vcc, 0x24000, v30
	s_nop 1
	v_addc_co_u32_e32 v35, vcc, 0, v31, vcc
	global_load_dword v96, v[34:35], off
	v_add_co_u32_e32 v32, vcc, 0x2a000, v30
	s_nop 1
	v_addc_co_u32_e32 v33, vcc, 0, v31, vcc
	global_load_dword v98, v[32:33], off
	v_add_co_u32_e32 v34, vcc, 0x30000, v30
	s_nop 1
	v_addc_co_u32_e32 v35, vcc, 0, v31, vcc
	global_load_dword v100, v[34:35], off
	v_add_co_u32_e32 v32, vcc, 0x36000, v30
	s_nop 1
	v_addc_co_u32_e32 v33, vcc, 0, v31, vcc
	global_load_dword v102, v[32:33], off
	v_add_co_u32_e32 v34, vcc, 0x3c000, v30
	s_nop 1
	v_addc_co_u32_e32 v35, vcc, 0, v31, vcc
	global_load_dword v104, v[34:35], off
	v_add_co_u32_e32 v32, vcc, 0x42000, v30
	s_nop 1
	v_addc_co_u32_e32 v33, vcc, 0, v31, vcc
	global_load_dword v106, v[32:33], off
	v_add_co_u32_e32 v34, vcc, 0x48000, v30
	s_nop 1
	v_addc_co_u32_e32 v35, vcc, 0, v31, vcc
	global_load_dword v108, v[34:35], off
	v_add_co_u32_e32 v32, vcc, 0x4e000, v30
	s_nop 1
	v_addc_co_u32_e32 v33, vcc, 0, v31, vcc
	global_load_dword v110, v[32:33], off
	v_add_co_u32_e32 v34, vcc, 0x54000, v30
	s_nop 1
	v_addc_co_u32_e32 v35, vcc, 0, v31, vcc
	global_load_dword v112, v[34:35], off
	v_add_co_u32_e32 v32, vcc, 0x5a000, v30
	s_nop 1
	v_addc_co_u32_e32 v33, vcc, 0, v31, vcc
	global_load_dword v114, v[32:33], off
	s_add_u32 s16, s16, 0x60000
	s_addc_u32 s17, s17, 0
	ds_read_b128 v[30:33], v4 offset:4096
	ds_read_b128 v[34:37], v4 offset:8192
	ds_read_b128 v[38:41], v4 offset:12288
	ds_read_b128 v[42:45], v4 offset:16384
	ds_read_b128 v[46:49], v4 offset:20480
	ds_read_b128 v[50:53], v4 offset:24576
	ds_read_b128 v[54:57], v4 offset:28672
	ds_read_b128 v[58:61], v4
	ds_read_b128 v[62:65], v4 offset:32768
	s_waitcnt lgkmcnt(8)
	v_mov_b32_e32 v75, v30
	s_waitcnt lgkmcnt(1)
	v_mov_b32_e32 v74, v58
	v_mov_b32_e32 v30, v59
	v_mov_b32_e32 v58, v60
	v_mov_b32_e32 v59, v32
	v_mov_b32_e32 v32, v61
	v_mov_b32_e32 v60, v34
	v_mov_b32_e32 v61, v38
	v_mov_b32_e32 v38, v35
	v_mov_b32_e32 v34, v36
	v_mov_b32_e32 v35, v40
	v_mov_b32_e32 v40, v37
	v_mov_b32_e32 v36, v42
	v_mov_b32_e32 v37, v46
	v_mov_b32_e32 v46, v43
	v_mov_b32_e32 v42, v44
	v_mov_b32_e32 v43, v48
	v_mov_b32_e32 v48, v45
	v_mov_b32_e32 v44, v50
	v_mov_b32_e32 v45, v54
	v_mov_b32_e32 v54, v51
	v_mov_b32_e32 v50, v52
	v_mov_b32_e32 v51, v56
	v_mov_b32_e32 v56, v53
	s_waitcnt vmcnt(15)
	v_pk_fma_f32 v[12:13], v[84:85], v[74:75], v[12:13] op_sel_hi:[0,1,1]
	v_pk_fma_f32 v[14:15], v[84:85], v[60:61], v[14:15] op_sel_hi:[0,1,1]
	v_pk_fma_f32 v[16:17], v[84:85], v[36:37], v[16:17] op_sel_hi:[0,1,1]
	v_pk_fma_f32 v[18:19], v[84:85], v[44:45], v[18:19] op_sel_hi:[0,1,1]
	s_waitcnt lgkmcnt(0)
	v_fmac_f32_e32 v29, v84, v62
	s_waitcnt vmcnt(14)
	v_pk_fma_f32 v[12:13], v[86:87], v[30:31], v[12:13] op_sel_hi:[0,1,1]
	v_pk_fma_f32 v[14:15], v[86:87], v[38:39], v[14:15] op_sel_hi:[0,1,1]
	v_pk_fma_f32 v[16:17], v[86:87], v[46:47], v[16:17] op_sel_hi:[0,1,1]
	v_pk_fma_f32 v[18:19], v[86:87], v[54:55], v[18:19] op_sel_hi:[0,1,1]
	v_fmac_f32_e32 v29, v86, v63
	s_waitcnt vmcnt(13)
	v_pk_fma_f32 v[12:13], v[88:89], v[58:59], v[12:13] op_sel_hi:[0,1,1]
	v_pk_fma_f32 v[14:15], v[88:89], v[34:35], v[14:15] op_sel_hi:[0,1,1]
	v_pk_fma_f32 v[16:17], v[88:89], v[42:43], v[16:17] op_sel_hi:[0,1,1]
	v_pk_fma_f32 v[18:19], v[88:89], v[50:51], v[18:19] op_sel_hi:[0,1,1]
	v_fmac_f32_e32 v29, v88, v64
	s_waitcnt vmcnt(12)
	v_pk_fma_f32 v[12:13], v[90:91], v[32:33], v[12:13] op_sel_hi:[0,1,1]
	v_pk_fma_f32 v[14:15], v[90:91], v[40:41], v[14:15] op_sel_hi:[0,1,1]
	v_pk_fma_f32 v[16:17], v[90:91], v[48:49], v[16:17] op_sel_hi:[0,1,1]
	v_pk_fma_f32 v[18:19], v[90:91], v[56:57], v[18:19] op_sel_hi:[0,1,1]
	v_fmac_f32_e32 v29, v90, v65
	ds_read_b128 v[30:33], v4 offset:4112
	ds_read_b128 v[34:37], v4 offset:8208
	ds_read_b128 v[38:41], v4 offset:12304
	ds_read_b128 v[42:45], v4 offset:16400
	ds_read_b128 v[46:49], v4 offset:20496
	ds_read_b128 v[50:53], v4 offset:24592
	ds_read_b128 v[54:57], v4 offset:28688
	ds_read_b128 v[58:61], v4 offset:16
	ds_read_b128 v[62:65], v4 offset:32784
	s_waitcnt lgkmcnt(8)
	v_mov_b32_e32 v75, v30
	s_waitcnt lgkmcnt(1)
	v_mov_b32_e32 v74, v58
	v_mov_b32_e32 v30, v59
	v_mov_b32_e32 v58, v60
	v_mov_b32_e32 v59, v32
	v_mov_b32_e32 v32, v61
	v_mov_b32_e32 v60, v34
	v_mov_b32_e32 v61, v38
	v_mov_b32_e32 v38, v35
	v_mov_b32_e32 v34, v36
	v_mov_b32_e32 v35, v40
	v_mov_b32_e32 v40, v37
	v_mov_b32_e32 v36, v42
	v_mov_b32_e32 v37, v46
	v_mov_b32_e32 v46, v43
	v_mov_b32_e32 v42, v44
	v_mov_b32_e32 v43, v48
	v_mov_b32_e32 v48, v45
	v_mov_b32_e32 v44, v50
	v_mov_b32_e32 v45, v54
	v_mov_b32_e32 v54, v51
	v_mov_b32_e32 v50, v52
	v_mov_b32_e32 v51, v56
	v_mov_b32_e32 v56, v53
	s_waitcnt vmcnt(11)
	v_pk_fma_f32 v[12:13], v[92:93], v[74:75], v[12:13] op_sel_hi:[0,1,1]
	v_pk_fma_f32 v[14:15], v[92:93], v[60:61], v[14:15] op_sel_hi:[0,1,1]
	v_pk_fma_f32 v[16:17], v[92:93], v[36:37], v[16:17] op_sel_hi:[0,1,1]
	v_pk_fma_f32 v[18:19], v[92:93], v[44:45], v[18:19] op_sel_hi:[0,1,1]
	s_waitcnt lgkmcnt(0)
; DI void phase0(const Params& p, char* smem) {
;     ...
;     for (int k = w * 128; k < w * 128 + 128; ++k) {
;       const float wv = wp[(size_t)k * 6144];
; #pragma unroll
;       for (int r = 0; r < 9; ++r) a[r] += sc[r * 1024 + k] * wv;
;     }
; #pragma unroll
;     for (int r = 0; r < 9; ++r) red[(w * 9 + r) * 64 + lane] = a[r];
;     __syncthreads();
	v_fmac_f32_e32 v29, v92, v62
	s_waitcnt vmcnt(10)
	v_pk_fma_f32 v[12:13], v[94:95], v[30:31], v[12:13] op_sel_hi:[0,1,1]
	v_pk_fma_f32 v[14:15], v[94:95], v[38:39], v[14:15] op_sel_hi:[0,1,1]
	v_pk_fma_f32 v[16:17], v[94:95], v[46:47], v[16:17] op_sel_hi:[0,1,1]
	v_pk_fma_f32 v[18:19], v[94:95], v[54:55], v[18:19] op_sel_hi:[0,1,1]
	v_fmac_f32_e32 v29, v94, v63
	s_waitcnt vmcnt(9)
	v_pk_fma_f32 v[12:13], v[96:97], v[58:59], v[12:13] op_sel_hi:[0,1,1]
	v_pk_fma_f32 v[14:15], v[96:97], v[34:35], v[14:15] op_sel_hi:[0,1,1]
	v_pk_fma_f32 v[16:17], v[96:97], v[42:43], v[16:17] op_sel_hi:[0,1,1]
	v_pk_fma_f32 v[18:19], v[96:97], v[50:51], v[18:19] op_sel_hi:[0,1,1]
	v_fmac_f32_e32 v29, v96, v64
	s_waitcnt vmcnt(8)
	v_pk_fma_f32 v[12:13], v[98:99], v[32:33], v[12:13] op_sel_hi:[0,1,1]
	v_pk_fma_f32 v[14:15], v[98:99], v[40:41], v[14:15] op_sel_hi:[0,1,1]
	v_pk_fma_f32 v[16:17], v[98:99], v[48:49], v[16:17] op_sel_hi:[0,1,1]
	v_pk_fma_f32 v[18:19], v[98:99], v[56:57], v[18:19] op_sel_hi:[0,1,1]
	v_fmac_f32_e32 v29, v98, v65
	ds_read_b128 v[30:33], v4 offset:4128
	ds_read_b128 v[34:37], v4 offset:8224
	ds_read_b128 v[38:41], v4 offset:12320
	ds_read_b128 v[42:45], v4 offset:16416
	ds_read_b128 v[46:49], v4 offset:20512
	ds_read_b128 v[50:53], v4 offset:24608
	ds_read_b128 v[54:57], v4 offset:28704
	ds_read_b128 v[58:61], v4 offset:32
	ds_read_b128 v[62:65], v4 offset:32800
	s_waitcnt lgkmcnt(8)
	v_mov_b32_e32 v75, v30
	s_waitcnt lgkmcnt(1)
	v_mov_b32_e32 v74, v58
	v_mov_b32_e32 v30, v59
	v_mov_b32_e32 v58, v60
	v_mov_b32_e32 v59, v32
	v_mov_b32_e32 v32, v61
	v_mov_b32_e32 v60, v34
	v_mov_b32_e32 v61, v38
	v_mov_b32_e32 v38, v35
	v_mov_b32_e32 v34, v36
	v_mov_b32_e32 v35, v40
	v_mov_b32_e32 v40, v37
	v_mov_b32_e32 v36, v42
	v_mov_b32_e32 v37, v46
	v_mov_b32_e32 v46, v43
	v_mov_b32_e32 v42, v44
	v_mov_b32_e32 v43, v48
	v_mov_b32_e32 v48, v45
	v_mov_b32_e32 v44, v50
	v_mov_b32_e32 v45, v54
	v_mov_b32_e32 v54, v51
	v_mov_b32_e32 v50, v52
	v_mov_b32_e32 v51, v56
	v_mov_b32_e32 v56, v53
	s_waitcnt vmcnt(7)
	v_pk_fma_f32 v[12:13], v[100:101], v[74:75], v[12:13] op_sel_hi:[0,1,1]
	v_pk_fma_f32 v[14:15], v[100:101], v[60:61], v[14:15] op_sel_hi:[0,1,1]
	v_pk_fma_f32 v[16:17], v[100:101], v[36:37], v[16:17] op_sel_hi:[0,1,1]
	v_pk_fma_f32 v[18:19], v[100:101], v[44:45], v[18:19] op_sel_hi:[0,1,1]
	s_waitcnt lgkmcnt(0)
	v_fmac_f32_e32 v29, v100, v62
	s_waitcnt vmcnt(6)
	v_pk_fma_f32 v[12:13], v[102:103], v[30:31], v[12:13] op_sel_hi:[0,1,1]
	v_pk_fma_f32 v[14:15], v[102:103], v[38:39], v[14:15] op_sel_hi:[0,1,1]
	v_pk_fma_f32 v[16:17], v[102:103], v[46:47], v[16:17] op_sel_hi:[0,1,1]
	v_pk_fma_f32 v[18:19], v[102:103], v[54:55], v[18:19] op_sel_hi:[0,1,1]
	v_fmac_f32_e32 v29, v102, v63
	s_waitcnt vmcnt(5)
	v_pk_fma_f32 v[12:13], v[104:105], v[58:59], v[12:13] op_sel_hi:[0,1,1]
	v_pk_fma_f32 v[14:15], v[104:105], v[34:35], v[14:15] op_sel_hi:[0,1,1]
	v_pk_fma_f32 v[16:17], v[104:105], v[42:43], v[16:17] op_sel_hi:[0,1,1]
	v_pk_fma_f32 v[18:19], v[104:105], v[50:51], v[18:19] op_sel_hi:[0,1,1]
	v_fmac_f32_e32 v29, v104, v64
	s_waitcnt vmcnt(4)
	v_pk_fma_f32 v[12:13], v[106:107], v[32:33], v[12:13] op_sel_hi:[0,1,1]
	v_pk_fma_f32 v[14:15], v[106:107], v[40:41], v[14:15] op_sel_hi:[0,1,1]
	v_pk_fma_f32 v[16:17], v[106:107], v[48:49], v[16:17] op_sel_hi:[0,1,1]
	v_pk_fma_f32 v[18:19], v[106:107], v[56:57], v[18:19] op_sel_hi:[0,1,1]
	v_fmac_f32_e32 v29, v106, v65
	ds_read_b128 v[30:33], v4 offset:4144
	ds_read_b128 v[34:37], v4 offset:8240
	ds_read_b128 v[38:41], v4 offset:12336
	ds_read_b128 v[42:45], v4 offset:16432
	ds_read_b128 v[46:49], v4 offset:20528
	ds_read_b128 v[50:53], v4 offset:24624
	ds_read_b128 v[54:57], v4 offset:28720
	ds_read_b128 v[58:61], v4 offset:48
	ds_read_b128 v[62:65], v4 offset:32816
	s_waitcnt lgkmcnt(8)
	v_mov_b32_e32 v75, v30
	s_waitcnt lgkmcnt(1)
	v_mov_b32_e32 v74, v58
	v_mov_b32_e32 v30, v59
	v_mov_b32_e32 v58, v60
	v_mov_b32_e32 v59, v32
	v_mov_b32_e32 v32, v61
	v_mov_b32_e32 v60, v34
	v_mov_b32_e32 v61, v38
	v_mov_b32_e32 v38, v35
	v_mov_b32_e32 v34, v36
	v_mov_b32_e32 v35, v40
	v_mov_b32_e32 v40, v37
	v_mov_b32_e32 v36, v42
	v_mov_b32_e32 v37, v46
	v_mov_b32_e32 v46, v43
	v_mov_b32_e32 v42, v44
	v_mov_b32_e32 v43, v48
	v_mov_b32_e32 v48, v45
	v_mov_b32_e32 v44, v50
	v_mov_b32_e32 v45, v54
	v_mov_b32_e32 v54, v51
	v_mov_b32_e32 v50, v52
	v_mov_b32_e32 v51, v56
	v_mov_b32_e32 v56, v53
	s_waitcnt vmcnt(3)
	v_pk_fma_f32 v[12:13], v[108:109], v[74:75], v[12:13] op_sel_hi:[0,1,1]
	v_pk_fma_f32 v[14:15], v[108:109], v[60:61], v[14:15] op_sel_hi:[0,1,1]
	v_pk_fma_f32 v[16:17], v[108:109], v[36:37], v[16:17] op_sel_hi:[0,1,1]
	v_pk_fma_f32 v[18:19], v[108:109], v[44:45], v[18:19] op_sel_hi:[0,1,1]
	s_waitcnt lgkmcnt(0)
	v_fmac_f32_e32 v29, v108, v62
	s_waitcnt vmcnt(2)
	v_pk_fma_f32 v[12:13], v[110:111], v[30:31], v[12:13] op_sel_hi:[0,1,1]
	v_pk_fma_f32 v[14:15], v[110:111], v[38:39], v[14:15] op_sel_hi:[0,1,1]
	v_pk_fma_f32 v[16:17], v[110:111], v[46:47], v[16:17] op_sel_hi:[0,1,1]
	v_pk_fma_f32 v[18:19], v[110:111], v[54:55], v[18:19] op_sel_hi:[0,1,1]
	v_fmac_f32_e32 v29, v110, v63
	s_waitcnt vmcnt(1)
	v_pk_fma_f32 v[12:13], v[112:113], v[58:59], v[12:13] op_sel_hi:[0,1,1]
	v_pk_fma_f32 v[14:15], v[112:113], v[34:35], v[14:15] op_sel_hi:[0,1,1]
	v_pk_fma_f32 v[16:17], v[112:113], v[42:43], v[16:17] op_sel_hi:[0,1,1]
	v_pk_fma_f32 v[18:19], v[112:113], v[50:51], v[18:19] op_sel_hi:[0,1,1]
	v_fmac_f32_e32 v29, v112, v64
	s_waitcnt vmcnt(0)
	v_pk_fma_f32 v[12:13], v[114:115], v[32:33], v[12:13] op_sel_hi:[0,1,1]
	v_pk_fma_f32 v[14:15], v[114:115], v[40:41], v[14:15] op_sel_hi:[0,1,1]
	v_pk_fma_f32 v[16:17], v[114:115], v[48:49], v[16:17] op_sel_hi:[0,1,1]
	v_pk_fma_f32 v[18:19], v[114:115], v[56:57], v[18:19] op_sel_hi:[0,1,1]
	v_fmac_f32_e32 v29, v114, v65
	v_add_u32_e32 v4, 64, v4
	s_cmp_eq_u32 s16, 0x300000
	s_cbranch_scc0 .LBB0_36
	ds_write2st64_b32 v26, v12, v13 offset0:144 offset1:145
	ds_write2st64_b32 v26, v14, v15 offset0:146 offset1:147
	ds_write2st64_b32 v26, v16, v17 offset0:148 offset1:149
	ds_write2st64_b32 v26, v18, v19 offset0:150 offset1:151
	ds_write_b32 v26, v29 offset:38912
	s_waitcnt lgkmcnt(0)
	s_barrier
	s_and_saveexec_b64 s[16:17], s[4:5]
	s_cbranch_execz .LBB0_20
	s_mul_i32 s18, s15, 0x1800
	s_add_i32 s19, s18, s14
	v_or_b32_e32 v10, s19, v1
	s_mul_i32 s18, s15, 9
	s_ashr_i32 s15, s14, 31
	v_ashrrev_i32_e32 v11, 31, v10
	v_lshl_add_u64 v[10:11], v[10:11], 2, s[90:91]
	v_lshl_add_u64 v[12:13], s[14:15], 2, v[6:7]
	s_mov_b64 s[14:15], 0
	v_mov_b32_e32 v4, v2
